# adaLN pass 0 (P1) loads hoisted as well
# baseline (speedup 1.0000x reference)
.LBB0_405:
	s_or_b64 exec, exec, s[48:49]
	v_lshl_add_u64 v[2:3], v[2:3], 0, v[12:13]
	global_load_dwordx4 v[30:33], v[2:3], off
	global_load_dwordx4 v[34:37], v[2:3], off offset:1024
	global_load_dwordx4 v[38:41], v[2:3], off offset:2048
	s_nop 0
	global_load_dwordx4 v[2:5], v[2:3], off offset:3072
	s_nop 0
	global_load_dwordx4 v[42:45], v[8:9], off
	global_load_dwordx4 v[78:81], v[8:9], off offset:1024
	global_load_dwordx4 v[90:93], v[8:9], off offset:2048
	global_load_dwordx4 v[102:105], v[8:9], off offset:3072
	v_min_i32_e32 v0, 0x4000, v6
	v_ashrrev_i32_e32 v0, 11, v0
	v_mul_hi_i32_i24_e32 v21, 0x9000, v0
	v_mul_i32_i24_e32 v20, 0x9000, v0
	v_lshl_add_u64 v[20:21], s[14:15], 0, v[20:21]
	v_lshl_add_u64 v[22:23], v[20:21], 0, s[38:39]
	v_lshl_add_u64 v[46:47], v[22:23], 0, v[12:13]
	global_load_dwordx4 v[82:85], v[46:47], off offset:1024
	global_load_dwordx4 v[94:97], v[46:47], off offset:2048
	global_load_dwordx4 v[106:109], v[46:47], off offset:3072
	global_load_dwordx4 v[46:49], v[46:47], off
	v_lshl_add_u64 v[54:55], v[20:21], 0, v[12:13]
	global_load_dwordx4 v[50:53], v[54:55], off
	global_load_dwordx4 v[86:89], v[54:55], off offset:1024
	global_load_dwordx4 v[98:101], v[54:55], off offset:2048
	global_load_dwordx4 v[110:113], v[54:55], off offset:3072
	s_mov_b32 s4, s42
	s_waitcnt vmcnt(15)
	v_mov_b32_e32 v56, v31
	s_waitcnt vmcnt(14)
	v_mov_b32_e32 v57, v35
	v_mov_b32_e32 v20, v30
	v_mov_b32_e32 v21, v34
	s_waitcnt vmcnt(13)
	v_mov_b32_e32 v64, v39
	s_waitcnt vmcnt(12)
	v_mov_b32_e32 v65, v3
	v_pk_mul_f32 v[56:57], v[56:57], v[56:57]
	v_mov_b32_e32 v58, v32
	v_mov_b32_e32 v59, v36
	v_mov_b32_e32 v62, v38
	v_mov_b32_e32 v63, v2
	v_pk_mul_f32 v[64:65], v[64:65], v[64:65]
	v_pk_fma_f32 v[20:21], v[20:21], v[20:21], v[56:57]
	v_mov_b32_e32 v60, v33
	v_mov_b32_e32 v61, v37
	v_mov_b32_e32 v66, v40
	v_mov_b32_e32 v67, v4
	v_pk_fma_f32 v[56:57], v[62:63], v[62:63], v[64:65]
	v_pk_fma_f32 v[20:21], v[58:59], v[58:59], v[20:21]
	v_mov_b32_e32 v68, v41
	v_mov_b32_e32 v69, v5
	v_pk_fma_f32 v[56:57], v[66:67], v[66:67], v[56:57]
	v_pk_fma_f32 v[20:21], v[60:61], v[60:61], v[20:21]
	v_pk_fma_f32 v[56:57], v[68:69], v[68:69], v[56:57]
	v_add_f32_e32 v0, v20, v21
	v_add_f32_e32 v0, v0, v56
	v_add_f32_e32 v0, v0, v57
	ds_bpermute_b32 v20, v24, v0
	s_waitcnt vmcnt(11)
	v_mov_b32_e32 v57, v44
	v_mov_b32_e32 v44, v43
	v_mov_b32_e32 v43, v32
	s_waitcnt vmcnt(4)
	v_mov_b32_e32 v32, v46
	s_waitcnt lgkmcnt(0)
	v_add_f32_e32 v0, v0, v20
	ds_bpermute_b32 v20, v25, v0
	s_waitcnt vmcnt(3)
	v_mov_b32_e32 v59, v52
	v_mov_b32_e32 v52, v51
	v_mov_b32_e32 v58, v50
	v_mov_b32_e32 v50, v34
	s_waitcnt lgkmcnt(0)
	v_add_f32_e32 v0, v0, v20
	ds_bpermute_b32 v56, v26, v0
	v_lshlrev_b64 v[20:21], 11, v[6:7]
	v_lshl_add_u64 v[20:21], v[10:11], 0, v[20:21]
	v_mov_b32_e32 v51, v36
	v_mov_b32_e32 v36, v35
	s_waitcnt lgkmcnt(0)
	v_add_f32_e32 v0, v0, v56
	ds_bpermute_b32 v7, v27, v0
	v_mov_b32_e32 v56, v42
	v_mov_b32_e32 v42, v30
	v_mov_b32_e32 v30, v31
	v_mov_b32_e32 v31, v33
	s_waitcnt lgkmcnt(0)
	v_add_f32_e32 v0, v0, v7
	ds_bpermute_b32 v7, v28, v0
	v_mov_b32_e32 v33, v48
	v_mov_b32_e32 v48, v47
	v_pk_add_f32 v[46:47], v[48:49], 1.0 op_sel_hi:[1,0]
	v_pk_add_f32 v[32:33], v[32:33], 1.0 op_sel_hi:[1,0]
	s_waitcnt lgkmcnt(0)
	v_add_f32_e32 v0, v0, v7
	ds_bpermute_b32 v7, v29, v0
	s_waitcnt lgkmcnt(0)
	v_add_f32_e32 v0, v0, v7
	v_fmamk_f32 v0, v0, 0x3a800000, v174
	v_mul_f32_e32 v7, 0x4b800000, v0
	v_cmp_gt_f32_e32 vcc, s27, v0
	s_nop 1
	v_cndmask_b32_e32 v0, v0, v7, vcc
	v_rsq_f32_e32 v0, v0
	s_nop 0
	v_mul_f32_e32 v7, 0x45800000, v0
	v_cndmask_b32_e32 v0, v0, v7, vcc
	v_pk_mul_f32 v[30:31], v[30:31], v[0:1] op_sel_hi:[1,0]
	v_pk_mul_f32 v[42:43], v[42:43], v[0:1] op_sel_hi:[1,0]
	v_pk_mul_f32 v[30:31], v[44:45], v[30:31]
	v_pk_mul_f32 v[42:43], v[56:57], v[42:43]
	v_pk_fma_f32 v[30:31], v[46:47], v[30:31], v[52:53]
	v_pk_fma_f32 v[32:33], v[32:33], v[42:43], v[58:59]
	v_and_b32_sdwa v43, v31, v177 dst_sel:DWORD dst_unused:UNUSED_PAD src0_sel:WORD_1 src1_sel:DWORD
	v_and_b32_sdwa v44, v30, v177 dst_sel:DWORD dst_unused:UNUSED_PAD src0_sel:WORD_1 src1_sel:DWORD
	v_and_b32_sdwa v7, v33, v177 dst_sel:DWORD dst_unused:UNUSED_PAD src0_sel:WORD_1 src1_sel:DWORD
	v_and_b32_sdwa v42, v32, v177 dst_sel:DWORD dst_unused:UNUSED_PAD src0_sel:WORD_1 src1_sel:DWORD
	v_add3_u32 v31, v31, v43, s28
	v_add3_u32 v30, v30, v44, s28
	v_add3_u32 v32, v32, v42, s28
	v_add3_u32 v7, v33, v7, s28
	v_and_b32_e32 v31, 0xffff0000, v31
	v_and_b32_e32 v30, 0xffff0000, v30
	v_or_b32_sdwa v31, v31, v7 dst_sel:DWORD dst_unused:UNUSED_PAD src0_sel:DWORD src1_sel:WORD_1
	v_or_b32_sdwa v30, v30, v32 dst_sel:DWORD dst_unused:UNUSED_PAD src0_sel:DWORD src1_sel:WORD_1
	global_store_dwordx2 v[20:21], v[30:31], off
	v_lshl_add_u64 v[42:43], v[22:23], 0, v[14:15]
	s_waitcnt vmcnt(1)
	v_mov_b32_e32 v46, v86
	v_mov_b32_e32 v47, v87
	v_mov_b32_e32 v48, v88
	v_mov_b32_e32 v49, v89
	v_mov_b32_e32 v42, v82
	v_mov_b32_e32 v43, v83
	v_mov_b32_e32 v44, v84
	v_mov_b32_e32 v45, v85
	v_mov_b32_e32 v30, v78
	v_mov_b32_e32 v31, v79
	v_mov_b32_e32 v32, v80
	v_mov_b32_e32 v33, v81
	v_pk_mul_f32 v[34:35], v[50:51], v[0:1] op_sel_hi:[1,0]
	v_pk_mul_f32 v[36:37], v[36:37], v[0:1] op_sel_hi:[1,0]
	v_mov_b32_e32 v50, v30
	v_mov_b32_e32 v51, v32
	v_mov_b32_e32 v52, v42
	v_mov_b32_e32 v53, v44
	v_mov_b32_e32 v32, v31
	v_mov_b32_e32 v44, v43
	v_mov_b32_e32 v56, v46
	v_mov_b32_e32 v57, v48
	v_mov_b32_e32 v48, v47
	v_pk_mul_f32 v[30:31], v[34:35], v[50:51]
	v_pk_add_f32 v[34:35], v[52:53], 1.0 op_sel_hi:[1,0]
	v_pk_mul_f32 v[32:33], v[36:37], v[32:33]
	v_pk_add_f32 v[36:37], v[44:45], 1.0 op_sel_hi:[1,0]
	v_pk_fma_f32 v[30:31], v[30:31], v[34:35], v[56:57]
	v_pk_fma_f32 v[32:33], v[32:33], v[36:37], v[48:49]
	v_and_b32_sdwa v7, v31, v177 dst_sel:DWORD dst_unused:UNUSED_PAD src0_sel:WORD_1 src1_sel:DWORD
	v_and_b32_sdwa v35, v33, v177 dst_sel:DWORD dst_unused:UNUSED_PAD src0_sel:WORD_1 src1_sel:DWORD
	v_and_b32_sdwa v36, v32, v177 dst_sel:DWORD dst_unused:UNUSED_PAD src0_sel:WORD_1 src1_sel:DWORD
	v_and_b32_sdwa v34, v30, v177 dst_sel:DWORD dst_unused:UNUSED_PAD src0_sel:WORD_1 src1_sel:DWORD
	v_add3_u32 v7, v31, v7, s28
	v_add3_u32 v31, v33, v35, s28
	v_add3_u32 v32, v32, v36, s28
	v_add3_u32 v30, v30, v34, s28
	v_and_b32_e32 v31, 0xffff0000, v31
	v_and_b32_e32 v32, 0xffff0000, v32
	v_or_b32_sdwa v31, v31, v7 dst_sel:DWORD dst_unused:UNUSED_PAD src0_sel:DWORD src1_sel:WORD_1
	v_or_b32_sdwa v30, v32, v30 dst_sel:DWORD dst_unused:UNUSED_PAD src0_sel:DWORD src1_sel:WORD_1
	global_store_dwordx2 v[20:21], v[30:31], off offset:512
	v_lshl_add_u64 v[34:35], v[22:23], 0, v[16:17]
	v_mov_b32_e32 v42, v98
	v_mov_b32_e32 v43, v99
	v_mov_b32_e32 v44, v100
	v_mov_b32_e32 v45, v101
	v_mov_b32_e32 v34, v94
	v_mov_b32_e32 v35, v95
	v_mov_b32_e32 v36, v96
	v_mov_b32_e32 v37, v97
	v_mov_b32_e32 v30, v90
	v_mov_b32_e32 v31, v91
	v_mov_b32_e32 v32, v92
	v_mov_b32_e32 v33, v93
	v_mov_b32_e32 v46, v38
	v_mov_b32_e32 v47, v40
	v_mov_b32_e32 v38, v39
	v_mov_b32_e32 v39, v41
	v_pk_mul_f32 v[40:41], v[46:47], v[0:1] op_sel_hi:[1,0]
	v_pk_mul_f32 v[38:39], v[38:39], v[0:1] op_sel_hi:[1,0]
	v_lshl_add_u64 v[22:23], v[22:23], 0, v[18:19]
	v_mov_b32_e32 v46, v30
	v_mov_b32_e32 v47, v32
	v_mov_b32_e32 v48, v34
	v_mov_b32_e32 v49, v36
	v_mov_b32_e32 v32, v31
	v_mov_b32_e32 v36, v35
	v_mov_b32_e32 v50, v42
	v_mov_b32_e32 v51, v44
	v_mov_b32_e32 v44, v43
	v_pk_mul_f32 v[30:31], v[40:41], v[46:47]
	v_pk_add_f32 v[34:35], v[48:49], 1.0 op_sel_hi:[1,0]
	v_pk_mul_f32 v[32:33], v[38:39], v[32:33]
	v_pk_add_f32 v[36:37], v[36:37], 1.0 op_sel_hi:[1,0]
	v_pk_fma_f32 v[30:31], v[30:31], v[34:35], v[50:51]
	v_pk_fma_f32 v[32:33], v[32:33], v[36:37], v[44:45]
	v_and_b32_sdwa v7, v31, v177 dst_sel:DWORD dst_unused:UNUSED_PAD src0_sel:WORD_1 src1_sel:DWORD
	v_and_b32_sdwa v35, v33, v177 dst_sel:DWORD dst_unused:UNUSED_PAD src0_sel:WORD_1 src1_sel:DWORD
	v_and_b32_sdwa v36, v32, v177 dst_sel:DWORD dst_unused:UNUSED_PAD src0_sel:WORD_1 src1_sel:DWORD
	v_and_b32_sdwa v34, v30, v177 dst_sel:DWORD dst_unused:UNUSED_PAD src0_sel:WORD_1 src1_sel:DWORD
	v_add3_u32 v7, v31, v7, s28
	v_add3_u32 v31, v33, v35, s28
	v_add3_u32 v32, v32, v36, s28
	v_add3_u32 v30, v30, v34, s28
	v_and_b32_e32 v31, 0xffff0000, v31
	v_and_b32_e32 v32, 0xffff0000, v32
	v_or_b32_sdwa v31, v31, v7 dst_sel:DWORD dst_unused:UNUSED_PAD src0_sel:DWORD src1_sel:WORD_1
	v_or_b32_sdwa v30, v32, v30 dst_sel:DWORD dst_unused:UNUSED_PAD src0_sel:DWORD src1_sel:WORD_1
	global_store_dwordx2 v[20:21], v[30:31], off offset:1024
	v_mov_b32_e32 v38, v110
	v_mov_b32_e32 v39, v111
	v_mov_b32_e32 v40, v112
	v_mov_b32_e32 v41, v113
	v_mov_b32_e32 v34, v106
	v_mov_b32_e32 v35, v107
	v_mov_b32_e32 v36, v108
	v_mov_b32_e32 v37, v109
	v_mov_b32_e32 v30, v102
	v_mov_b32_e32 v31, v103
	v_mov_b32_e32 v32, v104
	v_mov_b32_e32 v33, v105
	v_mov_b32_e32 v22, v2
	v_mov_b32_e32 v23, v4
	v_mov_b32_e32 v4, v3
	v_pk_mul_f32 v[2:3], v[22:23], v[0:1] op_sel_hi:[1,0]
	v_pk_mul_f32 v[4:5], v[4:5], v[0:1] op_sel_hi:[1,0]
	v_mov_b32_e32 v42, v34
	v_mov_b32_e32 v22, v30
	v_mov_b32_e32 v23, v32
	v_mov_b32_e32 v43, v36
	v_mov_b32_e32 v32, v31
	v_mov_b32_e32 v36, v35
	v_mov_b32_e32 v44, v38
	v_mov_b32_e32 v45, v40
	v_mov_b32_e32 v40, v39
	v_pk_mul_f32 v[2:3], v[2:3], v[22:23]
	v_pk_add_f32 v[22:23], v[42:43], 1.0 op_sel_hi:[1,0]
	v_pk_mul_f32 v[4:5], v[4:5], v[32:33]
	v_pk_add_f32 v[30:31], v[36:37], 1.0 op_sel_hi:[1,0]
	v_pk_fma_f32 v[2:3], v[2:3], v[22:23], v[44:45]
	v_pk_fma_f32 v[4:5], v[4:5], v[30:31], v[40:41]
	v_and_b32_sdwa v0, v3, v177 dst_sel:DWORD dst_unused:UNUSED_PAD src0_sel:WORD_1 src1_sel:DWORD
	v_and_b32_sdwa v22, v5, v177 dst_sel:DWORD dst_unused:UNUSED_PAD src0_sel:WORD_1 src1_sel:DWORD
	v_and_b32_sdwa v23, v4, v177 dst_sel:DWORD dst_unused:UNUSED_PAD src0_sel:WORD_1 src1_sel:DWORD
	v_and_b32_sdwa v7, v2, v177 dst_sel:DWORD dst_unused:UNUSED_PAD src0_sel:WORD_1 src1_sel:DWORD
	v_add3_u32 v0, v3, v0, s28
	v_add3_u32 v3, v5, v22, s28
	v_add3_u32 v4, v4, v23, s28
	v_add3_u32 v2, v2, v7, s28
	v_and_b32_e32 v3, 0xffff0000, v3
	v_and_b32_e32 v4, 0xffff0000, v4
	v_or_b32_sdwa v3, v3, v0 dst_sel:DWORD dst_unused:UNUSED_PAD src0_sel:DWORD src1_sel:WORD_1
	v_or_b32_sdwa v2, v4, v2 dst_sel:DWORD dst_unused:UNUSED_PAD src0_sel:DWORD src1_sel:WORD_1
	global_store_dwordx2 v[20:21], v[2:3], off offset:1536
	s_nop 0
	v_lshl_add_u32 v6, s4, 3, v6
	v_cmp_lt_i32_e32 vcc, s29, v6
	s_or_b64 s[46:47], vcc, s[46:47]
	s_andn2_b64 exec, exec, s[46:47]
	s_cbranch_execz .LBB0_410
